# P4 order swap: workgroups with id bit 3 set run GLA pass 3 before their attention units so only half the chip is in the bandwidth-bound part at a time
# speedup vs baseline: 1.0062x; 1.0062x over previous
; #define FRESH() const int lane = fresh_lane(); int wave = wave_s; asm volatile("" : "+s"(wave)); const int tid = wave * 64 + lane; (void)tid; unsigned char* ws = p.ws; asm volatile("" : "+s"(ws)); (void)ws; Params pl = p; pl.ws = ws; (void)pl
; __global__ void __launch_bounds__(512, 2) hymba_fwd(Params p) {
;     ...
;         for (int pr = vcu; pr < ((DUPMASK & 64) ? 512 : 256); pr += G) {
;             const int bh = (pr >> 4) & 15, i = pr & 15;
;             { FRESH(); attn_unit(p, bh >> 2, bh & 3, 31 - i, lds, tid, lane, wave); }
;             { FRESH(); attn_unit(p, bh >> 2, bh & 3, i, lds, tid, lane, wave); }
;         }
;     ...
;         { FRESH(); gla_pass<true>(p, l, lds, tid, lane, wave, bx, G, (DUPMASK & 128) ? 2048 : 1024); }
.LBB0_422:
	s_or_b64 exec, exec, s[0:1]
	v_readlane_b32 s0, v254, 46
	v_readlane_b32 s1, v254, 47
	s_andn2_b64 vcc, exec, s[0:1]
	s_mov_b32 s72, s89
	s_mov_b32 s73, s89
	s_waitcnt lgkmcnt(0)
	s_barrier
	s_bitcmp1_b32 s91, 3
	s_cselect_b32 s0, 1, 0
	v_writelane_b32 v255, s0, 62
	s_cbranch_scc1 .LBB0_423
	s_cbranch_vccz .LBB0_426

; #define FRESH() const int lane = fresh_lane(); int wave = wave_s; asm volatile("" : "+s"(wave)); const int tid = wave * 64 + lane; (void)tid; unsigned char* ws = p.ws; asm volatile("" : "+s"(ws)); (void)ws; Params pl = p; pl.ws = ws; (void)pl
; __global__ void __launch_bounds__(512, 2) hymba_fwd(Params p) {
;     ...
;         for (int pr = vcu; pr < ((DUPMASK & 64) ? 512 : 256); pr += G) {
;             const int bh = (pr >> 4) & 15, i = pr & 15;
;             { FRESH(); attn_unit(p, bh >> 2, bh & 3, 31 - i, lds, tid, lane, wave); }
;             { FRESH(); attn_unit(p, bh >> 2, bh & 3, i, lds, tid, lane, wave); }
;         }
;     ...
;         { FRESH(); gla_pass<true>(p, l, lds, tid, lane, wave, bx, G, (DUPMASK & 128) ? 2048 : 1024); }
.LBB0_425:
	s_add_i32 s73, s73, s68
	s_add_i32 s72, s72, s68
	s_cmpk_gt_i32 s73, 0xff
	s_barrier
	s_cbranch_scc0 .LBB0_426
	v_readlane_b32 s0, v255, 62
	s_nop 3
	s_cmp_eq_u32 s0, 0
	s_cbranch_scc1 .LBB0_423
	s_mov_b32 s0, 2
	s_nop 0
	v_writelane_b32 v255, s0, 62
	s_branch .LBB0_465

; #define FRESH() const int lane = fresh_lane(); int wave = wave_s; asm volatile("" : "+s"(wave)); const int tid = wave * 64 + lane; (void)tid; unsigned char* ws = p.ws; asm volatile("" : "+s"(ws)); (void)ws; Params pl = p; pl.ws = ws; (void)pl
; __global__ void __launch_bounds__(512, 2) hymba_fwd(Params p) {
;     ...
;         for (int pr = vcu; pr < ((DUPMASK & 64) ? 512 : 256); pr += G) {
;             const int bh = (pr >> 4) & 15, i = pr & 15;
;             { FRESH(); attn_unit(p, bh >> 2, bh & 3, 31 - i, lds, tid, lane, wave); }
;             { FRESH(); attn_unit(p, bh >> 2, bh & 3, i, lds, tid, lane, wave); }
;         }
;     ...
;         { FRESH(); gla_pass<true>(p, l, lds, tid, lane, wave, bx, G, (DUPMASK & 128) ? 2048 : 1024); }
.LBB0_465:
	v_readlane_b32 s0, v255, 62
	s_nop 3
	s_cmp_lg_u32 s0, 1
	s_cbranch_scc1 .Lsw_end
	s_mov_b32 s0, 2
	s_nop 0
	v_writelane_b32 v255, s0, 62
	v_readlane_b32 s0, v254, 46
	v_readlane_b32 s1, v254, 47
	s_nop 3
	s_andn2_b64 vcc, exec, s[0:1]
	s_nop 1
	s_cbranch_vccz .LBB0_426
